# NSA attention steps: cross-lane row-max via v_permlane16/32_swap instead of ds_bpermute
# speedup vs baseline: 1.0596x; 1.0013x over previous
; DEVI void attn_step(AttnState& st, const bf16x8 (&qf)[2][2], const bfu* Ks, const bfu* Vt, int hi, int lo, int fr, int fq) {
;     ...
;   float scs[2];
; #pragma unroll
;   for (int g = 0; g < 2; ++g) {
;     float mx = NEGF;
; #pragma unroll
;     for (int ksub = 0; ksub < 4; ++ksub)
; #pragma unroll
;       for (int j = 0; j < 4; ++j) mx = fmaxf(mx, s[g][ksub][j]);
;     mx = fmaxf(mx, __shfl_xor(mx, 16));
;     mx = fmaxf(mx, __shfl_xor(mx, 32));
;     float mn = fmaxf(st.m[g], mx);
;     float sc = __builtin_amdgcn_exp2f(st.m[g] - mn);
; #pragma unroll
;     for (int ksub = 0; ksub < 4; ++ksub)
; #pragma unroll
;       for (int j = 0; j < 4; ++j) s[g][ksub][j] = __builtin_amdgcn_exp2f(s[g][ksub][j] - mn);
;     st.m[g] = mn;
;     scs[g] = sc;
;   }
;   if (__builtin_amdgcn_ballot_w64((scs[0] != 1.f) || (scs[1] != 1.f)) != 0ull) {
; #pragma unroll
;     for (int g = 0; g < 2; ++g) {
;       st.ol[g] *= scs[g];
; #pragma unroll
;       for (int dsub = 0; dsub < 4; ++dsub) st.o[g][dsub] *= scs[g];
;     }
;   }
.LBB0_513:
	s_mov_b32 s0, 0xf149f2ca
	v_max3_f32 v159, v110, s0, v111
	v_max3_f32 v159, v159, v112, v113
	v_max3_f32 v159, v159, v114, v115
	v_max3_f32 v159, v159, v116, v117
	v_max3_f32 v159, v159, v122, v123
	v_max3_f32 v159, v159, v124, v125
	v_max3_f32 v159, v159, v134, v135
	v_max3_f32 v159, v159, v136, v137
	v_max3_f32 v160, v118, s0, v119
	v_max3_f32 v160, v160, v120, v121
	v_max3_f32 v160, v160, v126, v127
	v_max3_f32 v160, v160, v128, v129
	v_max3_f32 v160, v160, v130, v131
	v_max3_f32 v160, v160, v132, v133
	v_max3_f32 v160, v160, v138, v139
	v_max3_f32 v160, v160, v140, v141
	v_mov_b32_e32 v161, v159
	v_mov_b32_e32 v246, v160
	s_nop 1
	v_permlane16_swap_b32_e32 v159, v161
	v_permlane16_swap_b32_e32 v160, v246
	v_max_f32_e32 v159, v159, v161
	v_max_f32_e32 v160, v160, v246
	v_mov_b32_e32 v161, v159
	v_mov_b32_e32 v246, v160
	s_nop 1
	v_permlane32_swap_b32_e32 v159, v161
	v_permlane32_swap_b32_e32 v160, v246
	v_max3_f32 v159, v152, v159, v161
	v_max3_f32 v160, v154, v160, v246
	v_sub_f32_e32 v152, v152, v159
	v_exp_f32_e32 v152, v152
	v_sub_f32_e32 v154, v154, v160
	v_exp_f32_e32 v154, v154
	v_cmp_neq_f32_e32 vcc, 1.0, v152
	s_nop 0
	v_cmp_neq_f32_e64 s[0:1], 1.0, v154
	s_or_b64 vcc, vcc, s[0:1]
	s_cbranch_vccz .LBB0_515
	v_pk_mul_f32 v[104:105], v[104:105], v[152:153] op_sel_hi:[1,0]
	v_pk_mul_f32 v[102:103], v[102:103], v[152:153] op_sel_hi:[1,0]
	v_pk_mul_f32 v[68:69], v[68:69], v[152:153] op_sel_hi:[1,0]
	v_pk_mul_f32 v[66:67], v[66:67], v[152:153] op_sel_hi:[1,0]
	v_pk_mul_f32 v[64:65], v[64:65], v[152:153] op_sel_hi:[1,0]
	v_pk_mul_f32 v[62:63], v[62:63], v[152:153] op_sel_hi:[1,0]
	v_pk_mul_f32 v[60:61], v[60:61], v[152:153] op_sel_hi:[1,0]
	v_pk_mul_f32 v[58:59], v[58:59], v[152:153] op_sel_hi:[1,0]
	v_pk_mul_f32 v[52:53], v[52:53], v[152:153] op_sel_hi:[1,0]
	v_pk_mul_f32 v[50:51], v[50:51], v[152:153] op_sel_hi:[1,0]
	v_pk_mul_f32 v[108:109], v[108:109], v[154:155] op_sel_hi:[1,0]
	v_pk_mul_f32 v[106:107], v[106:107], v[154:155] op_sel_hi:[1,0]
	v_pk_mul_f32 v[80:81], v[80:81], v[154:155] op_sel_hi:[1,0]
	v_pk_mul_f32 v[78:79], v[78:79], v[154:155] op_sel_hi:[1,0]
	v_pk_mul_f32 v[76:77], v[76:77], v[154:155] op_sel_hi:[1,0]
	v_pk_mul_f32 v[74:75], v[74:75], v[154:155] op_sel_hi:[1,0]
	v_pk_mul_f32 v[72:73], v[72:73], v[154:155] op_sel_hi:[1,0]
	v_pk_mul_f32 v[70:71], v[70:71], v[154:155] op_sel_hi:[1,0]
	v_pk_mul_f32 v[56:57], v[56:57], v[154:155] op_sel_hi:[1,0]
	v_pk_mul_f32 v[54:55], v[54:55], v[154:155] op_sel_hi:[1,0]

; DEVI void attn_step(AttnState& st, const bf16x8 (&qf)[2][2], const bfu* Ks, const bfu* Vt, int hi, int lo, int fr, int fq) {
;     ...
;   float scs[2];
; #pragma unroll
;   for (int g = 0; g < 2; ++g) {
;     float mx = NEGF;
; #pragma unroll
;     for (int ksub = 0; ksub < 4; ++ksub)
; #pragma unroll
;       for (int j = 0; j < 4; ++j) mx = fmaxf(mx, s[g][ksub][j]);
;     mx = fmaxf(mx, __shfl_xor(mx, 16));
;     mx = fmaxf(mx, __shfl_xor(mx, 32));
;     float mn = fmaxf(st.m[g], mx);
;     float sc = __builtin_amdgcn_exp2f(st.m[g] - mn);
; #pragma unroll
;     for (int ksub = 0; ksub < 4; ++ksub)
; #pragma unroll
;       for (int j = 0; j < 4; ++j) s[g][ksub][j] = __builtin_amdgcn_exp2f(s[g][ksub][j] - mn);
;     st.m[g] = mn;
;     scs[g] = sc;
;   }
;   if (__builtin_amdgcn_ballot_w64((scs[0] != 1.f) || (scs[1] != 1.f)) != 0ull) {
; #pragma unroll
;     for (int g = 0; g < 2; ++g) {
;       st.ol[g] *= scs[g];
; #pragma unroll
;       for (int dsub = 0; dsub < 4; ++dsub) st.o[g][dsub] *= scs[g];
;     }
;   }
.LBB0_523:
	s_mov_b32 s0, 0xf149f2ca
	v_max3_f32 v204, v142, s0, v143
	v_max3_f32 v204, v204, v144, v145
	v_max3_f32 v204, v204, v146, v147
	v_max3_f32 v204, v204, v148, v149
	v_max3_f32 v204, v204, v154, v155
	v_max3_f32 v204, v204, v156, v157
	v_max3_f32 v204, v204, v166, v167
	v_max3_f32 v204, v204, v168, v169
	v_max3_f32 v205, v150, s0, v151
	v_max3_f32 v205, v205, v152, v153
	v_max3_f32 v205, v205, v158, v159
	v_max3_f32 v205, v205, v160, v161
	v_max3_f32 v205, v205, v162, v163
	v_max3_f32 v205, v205, v164, v165
	v_max3_f32 v205, v205, v170, v171
	v_max3_f32 v205, v205, v172, v173
	v_mov_b32_e32 v206, v204
	v_mov_b32_e32 v246, v205
	s_nop 1
	v_permlane16_swap_b32_e32 v204, v206
	v_permlane16_swap_b32_e32 v205, v246
	v_max_f32_e32 v204, v204, v206
	v_max_f32_e32 v205, v205, v246
	v_mov_b32_e32 v206, v204
	v_mov_b32_e32 v246, v205
	s_nop 1
	v_permlane32_swap_b32_e32 v204, v206
	v_permlane32_swap_b32_e32 v205, v246
	v_max3_f32 v204, v198, v204, v206
	v_max3_f32 v205, v200, v205, v246
	v_sub_f32_e32 v198, v198, v204
	v_exp_f32_e32 v198, v198
	v_sub_f32_e32 v200, v200, v205
	v_exp_f32_e32 v200, v200
	v_cmp_neq_f32_e32 vcc, 1.0, v198
	s_nop 0
	v_cmp_neq_f32_e64 s[0:1], 1.0, v200
	s_or_b64 vcc, vcc, s[0:1]
	s_cbranch_vccz .LBB0_525
	v_pk_mul_f32 v[140:141], v[140:141], v[198:199] op_sel_hi:[1,0]
	v_pk_mul_f32 v[138:139], v[138:139], v[198:199] op_sel_hi:[1,0]
	v_pk_mul_f32 v[112:113], v[112:113], v[198:199] op_sel_hi:[1,0]
	v_pk_mul_f32 v[110:111], v[110:111], v[198:199] op_sel_hi:[1,0]
	v_pk_mul_f32 v[104:105], v[104:105], v[198:199] op_sel_hi:[1,0]
	v_pk_mul_f32 v[102:103], v[102:103], v[198:199] op_sel_hi:[1,0]
	v_pk_mul_f32 v[96:97], v[96:97], v[198:199] op_sel_hi:[1,0]
	v_pk_mul_f32 v[94:95], v[94:95], v[198:199] op_sel_hi:[1,0]
	v_pk_mul_f32 v[88:89], v[88:89], v[198:199] op_sel_hi:[1,0]
	v_pk_mul_f32 v[86:87], v[86:87], v[198:199] op_sel_hi:[1,0]
	v_pk_mul_f32 v[136:137], v[136:137], v[200:201] op_sel_hi:[1,0]
	v_pk_mul_f32 v[134:135], v[134:135], v[200:201] op_sel_hi:[1,0]
	v_pk_mul_f32 v[108:109], v[108:109], v[200:201] op_sel_hi:[1,0]
	v_pk_mul_f32 v[106:107], v[106:107], v[200:201] op_sel_hi:[1,0]
	v_pk_mul_f32 v[100:101], v[100:101], v[200:201] op_sel_hi:[1,0]
	v_pk_mul_f32 v[98:99], v[98:99], v[200:201] op_sel_hi:[1,0]
	v_pk_mul_f32 v[92:93], v[92:93], v[200:201] op_sel_hi:[1,0]
	v_pk_mul_f32 v[90:91], v[90:91], v[200:201] op_sel_hi:[1,0]
	v_pk_mul_f32 v[84:85], v[84:85], v[200:201] op_sel_hi:[1,0]
	v_pk_mul_f32 v[82:83], v[82:83], v[200:201] op_sel_hi:[1,0]
